# v59 with all code after the hyena loop shifted by 4 bytes (one s_nop at the hyena exit label) to test fetch-phase sensitivity
# speedup vs baseline: 1.0030x; 1.0030x over previous
; #define LANE_SWAP1(v) __builtin_bit_cast(float, __builtin_amdgcn_update_dpp(0, __builtin_bit_cast(int, (float)(v)), 0xB1, 0xf, 0xf, false))
; #define LANE_SWAP2U(v) ((unsigned)__builtin_amdgcn_update_dpp(0, (int)(v), 0x4E, 0xf, 0xf, false))
; DEV unsigned pk2(float lo, float hi) { return (unsigned)f2bf(lo) | ((unsigned)f2bf(hi) << 16); }
; DEV void hyena_units(int c0, int cstride, const bf16_t* UT, bf16_t* YHT, const unsigned* KF, const float* convw  , const float* convb  , const float* hyb  , LAS unsigned char* lds, int tid, bool abl = false) {
;     ...
; #pragma unroll
;         for (int i = 0; i < 8; ++i) {
;             const int t = tid + 512 * i, odd = tid & 1, hi = (tid >> 1) & 1;
;             const float xn0 = LANE_SWAP1(z[0][i].x), yn0 = LANE_SWAP1(z[0][i].y), xn1 = LANE_SWAP1(z[1][i].x), yn1 = LANE_SWAP1(z[1][i].y);
;             const unsigned A = odd ? pk2(yn0, z[0][i].y) : pk2(z[0][i].x, xn0);
;             const unsigned B = odd ? pk2(yn1, z[1][i].y) : pk2(z[1][i].x, xn1);
;             const unsigned recv = LANE_SWAP2U(hi ? A : B);
;             u32x2 w; w.x = hi ? recv : A; w.y = hi ? B : recv;
;             *(u32x2*)(YHT + ((size_t)((2 * hi + odd) * 1024 + c)) * 4096 + (t & ~3)) = w;
;         }
.LBB0_522:
	s_nop 0
	v_mov_b32_e32 v19, v20
	v_mov_b32_e32 v54, v20
	v_mov_b32_e32 v17, v20
	v_mov_b32_e32 v18, v20
	v_mov_b32_dpp v19, v24 quad_perm:[1,0,3,2] row_mask:0xf bank_mask:0xf
	v_mov_b32_dpp v54, v25 quad_perm:[1,0,3,2] row_mask:0xf bank_mask:0xf
	v_mov_b32_dpp v17, v38 quad_perm:[1,0,3,2] row_mask:0xf bank_mask:0xf
	v_mov_b32_dpp v18, v39 quad_perm:[1,0,3,2] row_mask:0xf bank_mask:0xf
	s_and_saveexec_b64 s[2:3], s[36:37]
	s_xor_b64 s[2:3], exec, s[2:3]
	s_mov_b32 s1, 0xffff0000
	v_bfe_u32 v16, v54, 16, 1
	v_add3_u32 v16, v54, v16, s17
	v_bfe_u32 v19, v25, 16, 1
	v_lshrrev_b32_e32 v16, 16, v16
	v_add3_u32 v19, v25, v19, s17
	v_and_or_b32 v16, v19, s1, v16
	s_or_saveexec_b64 s[2:3], s[2:3]
	v_readlane_b32 s20, v252, 10
	v_readlane_b32 s21, v252, 11
	s_movk_i32 s54, 0xffc0
	s_mov_b32 s56, 0xfe03f81
	s_xor_b64 exec, exec, s[2:3]
	v_bfe_u32 v16, v24, 16, 1
	v_add3_u32 v16, v24, v16, s17
	v_bfe_u32 v24, v19, 16, 1
	v_lshrrev_b32_e32 v16, 16, v16
	v_add3_u32 v19, v19, v24, s17
	v_and_or_b32 v16, v19, s1, v16
	s_or_b64 exec, exec, s[2:3]
	s_and_saveexec_b64 s[2:3], s[36:37]
	s_xor_b64 s[2:3], exec, s[2:3]
	v_bfe_u32 v17, v18, 16, 1
	v_add3_u32 v17, v18, v17, s17
	v_bfe_u32 v18, v39, 16, 1
	v_lshrrev_b32_e32 v17, 16, v17
	v_add3_u32 v18, v39, v18, s17
	v_and_or_b32 v19, v18, s1, v17
	s_or_saveexec_b64 s[2:3], s[2:3]
	s_load_dword s81, s[20:21], 0x100
	v_readlane_b32 s89, v255, 8
	s_xor_b64 exec, exec, s[2:3]
	v_bfe_u32 v18, v38, 16, 1
	v_add3_u32 v18, v38, v18, s17
	v_bfe_u32 v19, v17, 16, 1
	v_lshrrev_b32_e32 v18, 16, v18
	v_add3_u32 v17, v17, v19, s17
	v_and_or_b32 v19, v17, s1, v18
	s_or_b64 exec, exec, s[2:3]
	v_and_b32_e32 v17, 2, v21
	v_lshlrev_b32_e32 v18, 10, v21
	v_and_b32_e32 v18, 0xc00, v18
	v_cmp_eq_u32_e64 s[38:39], 0, v17
	v_add_u32_e32 v24, s78, v18
	v_mov_b32_e32 v38, v20
	v_cndmask_b32_e64 v17, v16, v19, s[38:39]
	v_ashrrev_i32_e32 v25, 31, v24
	v_readlane_b32 s2, v255, 20
	v_mov_b32_dpp v38, v17 quad_perm:[2,3,0,1] row_mask:0xf bank_mask:0xf
	v_lshlrev_b64 v[24:25], 13, v[24:25]
	v_readlane_b32 s3, v255, 21
	v_cndmask_b32_e64 v18, v38, v16, s[38:39]
	v_and_b32_e32 v16, -4, v21
	v_lshl_add_u64 v[24:25], s[2:3], 0, v[24:25]
	v_ashrrev_i32_e32 v17, 31, v16
	v_cndmask_b32_e64 v19, v19, v38, s[38:39]
	v_lshl_add_u64 v[16:17], v[16:17], 1, v[24:25]
	global_store_dwordx2 v[16:17], v[18:19], off
	v_mov_b32_e32 v25, v20
	v_mov_b32_e32 v38, 0
	v_mov_b32_e32 v19, 0
	v_mov_b32_e32 v24, 0
	v_mov_b32_dpp v25, v30 quad_perm:[1,0,3,2] row_mask:0xf bank_mask:0xf
	v_mov_b32_dpp v38, v31 quad_perm:[1,0,3,2] row_mask:0xf bank_mask:0xf
	v_mov_b32_dpp v19, v42 quad_perm:[1,0,3,2] row_mask:0xf bank_mask:0xf
	v_mov_b32_dpp v24, v43 quad_perm:[1,0,3,2] row_mask:0xf bank_mask:0xf
	s_and_saveexec_b64 s[2:3], s[36:37]
	s_xor_b64 s[2:3], exec, s[2:3]
	s_cbranch_execz .LBB0_532
	v_bfe_u32 v18, v38, 16, 1
	v_add3_u32 v18, v38, v18, s17
	v_bfe_u32 v25, v31, 16, 1
	v_lshrrev_b32_e32 v18, 16, v18
	v_add3_u32 v25, v31, v25, s17
	v_and_or_b32 v18, v25, s1, v18
	s_andn2_saveexec_b64 s[2:3], s[2:3]
	s_branch .LBB0_533
